# phase 8 runs one full round; its 288 leftover gate tiles run at the start of phase 9 on workgroups 0..287, qkv tiles split 2 vs 5-6 per workgroup
# speedup vs baseline: 1.0853x; 1.0052x over previous
_Z11mega_kernel6Params:
	s_add_u32 s60, s0, 0x118
	s_addc_u32 s61, s1, 0
	s_load_dwordx2 s[64:65], s[0:1], 0x118
	v_writelane_b32 v254, s0, 0
	v_and_b32_e32 v189, 0x3ff, v0
	s_mov_b32 s50, s2
	s_mov_b32 s100, 0
	v_writelane_b32 v254, s1, 1
	s_load_dwordx2 s[0:1], s[0:1], 0x90
	s_getreg_b32 s8, hwreg(HW_REG_XCC_ID, 0, 4)
	s_movk_i32 s54, 0x3ff
	s_mov_b32 s67, 0
	v_cmp_eq_u32_e64 s[56:57], 0, v189
	s_waitcnt lgkmcnt(0)
	v_mov_b64_e32 v[184:185], s[0:1]
	s_and_saveexec_b64 s[2:3], s[56:57]
	s_cbranch_execz .LBB0_4
	s_mov_b64 s[6:7], exec
	v_mbcnt_lo_u32_b32 v1, s6, 0
	v_mbcnt_hi_u32_b32 v1, s7, v1
	v_cmp_eq_u32_e32 vcc, 0, v1
	v_mov_b64_e32 v[184:185], s[0:1]
	s_and_saveexec_b64 s[4:5], vcc
	s_cbranch_execz .LBB0_3
	s_lshl_b32 s8, s8, 8
	s_and_b32 s8, s8, 0xf00
	s_add_u32 s8, s0, s8
	s_addc_u32 s9, s1, 0
	s_bcnt1_i32_b64 s6, s[6:7]
	v_mov_b32_e32 v1, 0xff00000
	v_mov_b32_e32 v2, s6
	global_atomic_add v1, v2, s[8:9] offset:1024
	v_mov_b64_e32 v[184:185], s[0:1]

.LBB0_60:
	s_and_b64 vcc, exec, s[0:1]
	s_cbranch_vccz .LBB0_88
	v_readlane_b32 s0, v254, 6
	v_readlane_b32 s1, v254, 7
	v_readfirstlane_b32 s12, v184
	v_readfirstlane_b32 s13, v185
	s_andn2_b64 vcc, exec, s[0:1]
	s_cbranch_vccnz .LBB0_88
	s_cmpk_lt_i32 s50, 0x120
	s_cbranch_scc0 .Lp9_setup
	s_mov_b32 s14, s12
	s_mov_b32 s15, s13
	s_add_u32 s16, s14, 0x4000000
	s_addc_u32 s17, s15, 0
	s_add_u32 s18, s14, 0x2100000
	s_addc_u32 s19, s15, 0
	s_add_u32 s20, s14, 0x1000000
	s_addc_u32 s21, s15, 0
	s_add_u32 s22, s14, 0x3e00000
	s_addc_u32 s23, s15, 0
	s_add_i32 s5, s50, 0x200
	s_lshl_b32 s4, s5, 8
	s_mov_b32 s100, 1
	s_branch .LBB0_95
.Lp9_after_gate:
	s_mov_b32 s100, 0
	v_readfirstlane_b32 s12, v184
	v_readfirstlane_b32 s13, v185
	s_nop 1
.Lp9_setup:
	s_add_u32 s14, s12, 0x800000
	s_addc_u32 s15, s13, 0
	s_add_u32 s16, s12, 0x2e00000
	s_addc_u32 s17, s13, 0
	s_add_u32 s18, s12, 0x3100000
	s_addc_u32 s19, s13, 0
	s_add_u32 s20, s12, 0x3e00000
	s_addc_u32 s21, s13, 0
	s_add_u32 s22, s12, 0x8000000
	s_addc_u32 s23, s13, 0
	s_add_u32 s4, s12, 0xb000000
	s_addc_u32 s5, s13, 0
	s_add_u32 s6, s12, 0xd000000
	s_addc_u32 s7, s13, 0
	s_mov_b32 s8, s50
	s_movk_i32 s101, 0x120
	s_movk_i32 s32, 0x23f
	s_cmpk_lt_i32 s50, 0x120
	s_cbranch_scc1 .Lp9_go
	s_add_i32 s8, s50, 0x120
	s_movk_i32 s101, 0xe0
	s_movk_i32 s32, 0x6ff
.Lp9_go:
	s_branch .LBB0_65

.LBB0_64:
	s_add_i32 s8, s8, s101
	s_cmp_gt_i32 s8, s32
	s_cbranch_scc1 .LBB0_88

.LBB0_94:
	s_cmp_eq_u32 s100, 1
	s_cbranch_scc1 .Lp9_after_gate
	s_add_i32 s5, s5, s64
	s_add_i32 s4, s4, s51
	s_cmpk_gt_i32 s5, 0x1ff
	s_cbranch_scc1 .LBB0_127

	.amdhsa_kernel _Z11mega_kernel6Params
		.amdhsa_group_segment_fixed_size 69632
		.amdhsa_private_segment_fixed_size 0
		.amdhsa_kernarg_size 536
		.amdhsa_user_sgpr_count 2
		.amdhsa_user_sgpr_dispatch_ptr 0
		.amdhsa_user_sgpr_queue_ptr 0
		.amdhsa_user_sgpr_kernarg_segment_ptr 1
		.amdhsa_user_sgpr_dispatch_id 0
		.amdhsa_user_sgpr_kernarg_preload_length 0
		.amdhsa_user_sgpr_kernarg_preload_offset 0
		.amdhsa_user_sgpr_private_segment_size 0
		.amdhsa_uses_dynamic_stack 0
		.amdhsa_enable_private_segment 0
		.amdhsa_system_sgpr_workgroup_id_x 1
		.amdhsa_system_sgpr_workgroup_id_y 0
		.amdhsa_system_sgpr_workgroup_id_z 0
		.amdhsa_system_sgpr_workgroup_info 0
		.amdhsa_system_vgpr_workitem_id 2
		.amdhsa_next_free_vgpr 256
		.amdhsa_next_free_sgpr 102
		.amdhsa_accum_offset 256
		.amdhsa_reserve_vcc 1
		.amdhsa_float_round_mode_32 0
		.amdhsa_float_round_mode_16_64 0
		.amdhsa_float_denorm_mode_32 3
		.amdhsa_float_denorm_mode_16_64 3
		.amdhsa_dx10_clamp 1
		.amdhsa_ieee_mode 1
		.amdhsa_fp16_overflow 0
		.amdhsa_tg_split 0
		.amdhsa_exception_fp_ieee_invalid_op 0
		.amdhsa_exception_fp_denorm_src 0
		.amdhsa_exception_fp_ieee_div_zero 0
		.amdhsa_exception_fp_ieee_overflow 0
		.amdhsa_exception_fp_ieee_underflow 0
		.amdhsa_exception_fp_ieee_inexact 0
		.amdhsa_exception_int_div_zero 0
	.end_amdhsa_kernel

amdhsa.kernels:
  - .agpr_count:     0
    .args:
      - .offset:         0
        .size:           280
        .value_kind:     by_value
      - .offset:         280
        .size:           4
        .value_kind:     hidden_block_count_x
      - .offset:         284
        .size:           4
        .value_kind:     hidden_block_count_y
      - .offset:         288
        .size:           4
        .value_kind:     hidden_block_count_z
      - .offset:         292
        .size:           2
        .value_kind:     hidden_group_size_x
      - .offset:         294
        .size:           2
        .value_kind:     hidden_group_size_y
      - .offset:         296
        .size:           2
        .value_kind:     hidden_group_size_z
      - .offset:         298
        .size:           2
        .value_kind:     hidden_remainder_x
      - .offset:         300
        .size:           2
        .value_kind:     hidden_remainder_y
      - .offset:         302
        .size:           2
        .value_kind:     hidden_remainder_z
      - .offset:         320
        .size:           8
        .value_kind:     hidden_global_offset_x
      - .offset:         328
        .size:           8
        .value_kind:     hidden_global_offset_y
      - .offset:         336
        .size:           8
        .value_kind:     hidden_global_offset_z
      - .offset:         344
        .size:           2
        .value_kind:     hidden_grid_dims
      - .offset:         368
        .size:           8
        .value_kind:     hidden_multigrid_sync_arg
    .group_segment_fixed_size: 69632
    .kernarg_segment_align: 8
    .kernarg_segment_size: 536
    .language:       OpenCL C
    .language_version:
      - 2
      - 0
    .max_flat_workgroup_size: 256
    .name:           _Z11mega_kernel6Params
    .private_segment_fixed_size: 0
    .sgpr_count:     108
    .sgpr_spill_count: 97
    .symbol:         _Z11mega_kernel6Params.kd
    .uniform_work_group_size: 1
    .uses_dynamic_stack: false
    .vgpr_count:     256
    .vgpr_spill_count: 0
    .wavefront_size: 64
